# attention: workgroup barrier at the end of each unit removed (K/V LDS buffers alternate and every unit has an even number of key-pair steps, so the next unit's first staging never touches the buffer s
# speedup vs baseline: 1.0098x; 1.0034x over previous
.LBB0_1069:
	v_mov_b32_e32 v38, v178
	s_nop 1
	v_permlane32_swap_b32_e32 v178, v38
	v_add_f32_e32 v38, v178, v38
	v_div_scale_f32 v39, s[12:13], v38, v38, 1.0
	v_rcp_f32_e32 v40, v39
	s_add_i32 s16, s16, 1
	s_add_i32 s17, s17, 4
	s_addk_i32 s18, 0xff00
	v_fma_f32 v41, -v39, v40, 1.0
	v_fmac_f32_e32 v40, v41, v40
	v_div_scale_f32 v41, vcc, 1.0, v38, 1.0
	v_mul_f32_e32 v42, v41, v40
	v_fma_f32 v43, -v39, v42, v41
	v_fmac_f32_e32 v42, v43, v40
	v_fma_f32 v39, -v39, v42, v41
	v_div_fmas_f32 v39, v39, v40, v42
	v_div_fixup_f32 v38, v39, v38, 1.0
	v_pk_mul_f32 v[0:1], v[0:1], v[38:39] op_sel_hi:[1,0]
	v_pk_mul_f32 v[2:3], v[2:3], v[38:39] op_sel_hi:[1,0]
	v_pk_mul_f32 v[4:5], v[4:5], v[38:39] op_sel_hi:[1,0]
	v_pk_mul_f32 v[6:7], v[6:7], v[38:39] op_sel_hi:[1,0]
	v_cvt_pk_bf16_f32 v0, v0, v1
	v_cvt_pk_bf16_f32 v1, v2, v3
	v_cvt_pk_bf16_f32 v4, v4, v5
	v_cvt_pk_bf16_f32 v5, v6, v7
	v_pk_mul_f32 v[2:3], v[16:17], v[38:39] op_sel_hi:[1,0]
	v_pk_mul_f32 v[16:17], v[18:19], v[38:39] op_sel_hi:[1,0]
	ds_write2_b64 v177, v[0:1], v[4:5] offset1:2
	v_pk_mul_f32 v[0:1], v[20:21], v[38:39] op_sel_hi:[1,0]
	v_pk_mul_f32 v[4:5], v[22:23], v[38:39] op_sel_hi:[1,0]
	v_cvt_pk_bf16_f32 v2, v2, v3
	v_cvt_pk_bf16_f32 v3, v16, v17
	v_cvt_pk_bf16_f32 v0, v0, v1
	v_cvt_pk_bf16_f32 v1, v4, v5
	ds_write2_b64 v177, v[2:3], v[0:1] offset0:8 offset1:10
	v_pk_mul_f32 v[0:1], v[8:9], v[38:39] op_sel_hi:[1,0]
	v_pk_mul_f32 v[2:3], v[10:11], v[38:39] op_sel_hi:[1,0]
	v_cvt_pk_bf16_f32 v0, v0, v1
	v_cvt_pk_bf16_f32 v1, v2, v3
	v_pk_mul_f32 v[2:3], v[24:25], v[38:39] op_sel_hi:[1,0]
	v_pk_mul_f32 v[4:5], v[26:27], v[38:39] op_sel_hi:[1,0]
	v_cvt_pk_bf16_f32 v2, v2, v3
	v_cvt_pk_bf16_f32 v3, v4, v5
	v_pk_mul_f32 v[4:5], v[12:13], v[38:39] op_sel_hi:[1,0]
	v_pk_mul_f32 v[6:7], v[14:15], v[38:39] op_sel_hi:[1,0]
	v_cvt_pk_bf16_f32 v4, v4, v5
	v_cvt_pk_bf16_f32 v5, v6, v7
	ds_write2_b64 v177, v[0:1], v[4:5] offset0:4 offset1:6
	v_pk_mul_f32 v[0:1], v[28:29], v[38:39] op_sel_hi:[1,0]
	v_pk_mul_f32 v[4:5], v[30:31], v[38:39] op_sel_hi:[1,0]
	v_cvt_pk_bf16_f32 v0, v0, v1
	v_cvt_pk_bf16_f32 v1, v4, v5
	ds_write2_b64 v177, v[2:3], v[0:1] offset0:12 offset1:14
	ds_read_b128 v[0:3], v175
	ds_read_b128 v[4:7], v175 offset:1152
	ds_read_b128 v[8:11], v175 offset:2304
	ds_read_b128 v[12:15], v175 offset:3456
	s_cmp_eq_u32 s16, 8
	v_lshl_add_u64 v[32:33], v[138:139], 0, s[4:5]
	v_lshl_add_u64 v[34:35], v[138:139], 0, s[6:7]
	v_lshl_add_u64 v[36:37], v[138:139], 0, s[8:9]
	s_waitcnt vmcnt(0) lgkmcnt(3)
	global_store_dwordx4 v[138:139], v[0:3], off
	s_waitcnt lgkmcnt(2)
	global_store_dwordx4 v[32:33], v[4:7], off
	s_waitcnt lgkmcnt(1)
	global_store_dwordx4 v[34:35], v[8:11], off
	s_waitcnt lgkmcnt(0)
	global_store_dwordx4 v[36:37], v[12:15], off
	s_cbranch_scc1 .LBB0_1075
